# statpf + EpiGate: second bias pair loaded at epilogue top into dead fragment VGPRs, mid-epilogue vmcnt(0) (stores+loads) removed
# speedup vs baseline: 1.0097x; 1.0097x over previous
.LBB0_1194:
	s_and_b64 vcc, exec, s[8:9]
	s_cbranch_vccz .LBB0_1140
	s_lshl_b32 s88, s13, 9
	s_lshl_b64 s[8:9], s[88:89], 2
	v_readlane_b32 s13, v254, 51
	s_add_u32 s8, s13, s8
	v_readlane_b32 s13, v255, 12
	s_addc_u32 s9, s13, s9
	v_lshl_add_u64 v[140:141], v[210:211], 2, s[8:9]
	global_load_dwordx4 v[134:137], v[140:141], off
	global_load_dwordx4 v[130:133], v[140:141], off offset:16
	global_load_dwordx4 v[150:153], v[140:141], off offset:512
	global_load_dwordx4 v[154:157], v[140:141], off offset:528
	s_lshl_b32 s8, s87, 2
	s_add_i32 s8, s8, s85
	s_ashr_i32 s9, s8, 31
	s_lshl_b64 s[8:9], s[8:9], 17
	v_lshl_add_u64 v[138:139], v[208:209], 0, s[8:9]
	s_movk_i32 s8, 0x2000
	v_add_co_u32_e32 v142, vcc, s8, v138
	s_movk_i32 s8, 0x4000
	s_nop 0
	v_addc_co_u32_e32 v143, vcc, 0, v139, vcc
	s_waitcnt vmcnt(0)
	v_pk_add_f32 v[126:127], v[126:127], v[134:135]
	s_nop 0
	v_mul_f32_e32 v0, 0xbfb8aa3b, v126
	v_mul_f32_e32 v126, 0xbfb8aa3b, v127
	v_exp_f32_e32 v0, v0
	v_exp_f32_e32 v126, v126
	v_pk_add_f32 v[114:115], v[114:115], v[130:131]
	v_pk_add_f32 v[106:107], v[106:107], v[130:131]
	v_mul_f32_e32 v114, 0xbfb8aa3b, v114
	v_exp_f32_e32 v114, v114
	v_add_f32_e32 v0, 1.0, v0
	v_add_f32_e32 v126, 1.0, v126
	v_rcp_f32_e32 v0, v0
	v_rcp_f32_e32 v126, v126
	v_pk_add_f32 v[128:129], v[128:129], v[136:137]
	v_pk_add_f32 v[124:125], v[124:125], v[132:133]
	v_pk_add_f32 v[122:123], v[122:123], v[130:131]
	v_mul_f32_e32 v106, 0xbfb8aa3b, v106
	v_pk_add_f32 v[120:121], v[120:121], v[136:137]
	v_pk_add_f32 v[118:119], v[118:119], v[134:135]
	v_pk_add_f32 v[116:117], v[116:117], v[132:133]
	v_mul_f32_e32 v127, 0xbfb8aa3b, v128
	v_mul_f32_e32 v128, 0xbfb8aa3b, v129
	v_mul_f32_e32 v122, 0xbfb8aa3b, v122
	v_mul_f32_e32 v123, 0xbfb8aa3b, v123
	v_mul_f32_e32 v124, 0xbfb8aa3b, v124
	v_mul_f32_e32 v125, 0xbfb8aa3b, v125
	v_exp_f32_e32 v106, v106
	v_mul_f32_e32 v107, 0xbfb8aa3b, v107
	v_mul_f32_e32 v118, 0xbfb8aa3b, v118
	v_mul_f32_e32 v119, 0xbfb8aa3b, v119
	v_mul_f32_e32 v120, 0xbfb8aa3b, v120
	v_mul_f32_e32 v121, 0xbfb8aa3b, v121
	v_mul_f32_e32 v115, 0xbfb8aa3b, v115
	v_mul_f32_e32 v116, 0xbfb8aa3b, v116
	v_mul_f32_e32 v117, 0xbfb8aa3b, v117
	v_exp_f32_e32 v127, v127
	v_exp_f32_e32 v128, v128
	v_exp_f32_e32 v122, v122
	v_exp_f32_e32 v123, v123
	v_exp_f32_e32 v124, v124
	v_exp_f32_e32 v125, v125
	v_add_f32_e32 v114, 1.0, v114
	v_pk_add_f32 v[110:111], v[110:111], v[134:135]
	v_exp_f32_e32 v107, v107
	v_exp_f32_e32 v118, v118
	v_exp_f32_e32 v119, v119
	v_exp_f32_e32 v120, v120
	v_exp_f32_e32 v121, v121
	v_exp_f32_e32 v115, v115
	v_exp_f32_e32 v116, v116
	v_exp_f32_e32 v117, v117
	v_rcp_f32_e32 v129, v114
	v_cvt_pk_bf16_f32 v114, v0, v126
	v_mul_f32_e32 v0, 0xbfb8aa3b, v110
	v_mul_f32_e32 v110, 0xbfb8aa3b, v111
	v_exp_f32_e32 v0, v0
	v_exp_f32_e32 v110, v110
	v_pk_add_f32 v[112:113], v[112:113], v[136:137]
	v_pk_add_f32 v[108:109], v[108:109], v[132:133]
	v_add_f32_e32 v106, 1.0, v106
	v_add_f32_e32 v127, 1.0, v127
	v_add_f32_e32 v128, 1.0, v128
	v_add_f32_e32 v122, 1.0, v122
	v_add_f32_e32 v123, 1.0, v123
	v_add_f32_e32 v124, 1.0, v124
	v_add_f32_e32 v125, 1.0, v125
	v_mul_f32_e32 v111, 0xbfb8aa3b, v112
	v_mul_f32_e32 v112, 0xbfb8aa3b, v113
	v_rcp_f32_e32 v113, v106
	v_add_f32_e32 v106, 1.0, v107
	v_mul_f32_e32 v107, 0xbfb8aa3b, v108
	v_add_f32_e32 v118, 1.0, v118
	v_add_f32_e32 v119, 1.0, v119
	v_add_f32_e32 v120, 1.0, v120
	v_add_f32_e32 v121, 1.0, v121
	v_add_f32_e32 v115, 1.0, v115
	v_add_f32_e32 v116, 1.0, v116
	v_add_f32_e32 v117, 1.0, v117
	v_rcp_f32_e32 v127, v127
	v_rcp_f32_e32 v128, v128
	v_rcp_f32_e32 v122, v122
	v_rcp_f32_e32 v123, v123
	v_rcp_f32_e32 v124, v124
	v_rcp_f32_e32 v125, v125
	v_exp_f32_e32 v107, v107
	v_mul_f32_e32 v108, 0xbfb8aa3b, v109
	v_rcp_f32_e32 v118, v118
	v_rcp_f32_e32 v119, v119
	v_rcp_f32_e32 v120, v120
	v_rcp_f32_e32 v121, v121
	v_rcp_f32_e32 v144, v115
	v_rcp_f32_e32 v145, v116
	v_rcp_f32_e32 v146, v117
	v_add_f32_e32 v0, 1.0, v0
	v_add_f32_e32 v110, 1.0, v110
	v_exp_f32_e32 v108, v108
	v_rcp_f32_e32 v0, v0
	v_rcp_f32_e32 v110, v110
	v_pk_add_f32 v[98:99], v[98:99], v[130:131]
	v_cvt_pk_bf16_f32 v115, v127, v128
	v_mul_f32_e32 v98, 0xbfb8aa3b, v98
	v_cvt_pk_bf16_f32 v116, v122, v123
	v_cvt_pk_bf16_f32 v117, v124, v125
	v_rcp_f32_e32 v109, v106
	v_add_f32_e32 v106, 1.0, v107
	v_exp_f32_e32 v98, v98
	v_mul_f32_e32 v99, 0xbfb8aa3b, v99
	v_cvt_pk_bf16_f32 v118, v118, v119
	v_cvt_pk_bf16_f32 v119, v120, v121
	v_cvt_pk_bf16_f32 v120, v129, v144
	v_cvt_pk_bf16_f32 v121, v145, v146
	global_store_dwordx4 v[138:139], v[114:117], off
	global_store_dwordx4 v[142:143], v[118:121], off
	v_exp_f32_e32 v111, v111
	v_exp_f32_e32 v112, v112
	v_rcp_f32_e32 v114, v106
	v_add_f32_e32 v106, 1.0, v108
	v_pk_add_f32 v[102:103], v[102:103], v[134:135]
	v_exp_f32_e32 v99, v99
	v_rcp_f32_e32 v115, v106
	v_cvt_pk_bf16_f32 v106, v0, v110
	v_mul_f32_e32 v0, 0xbfb8aa3b, v102
	v_mul_f32_e32 v102, 0xbfb8aa3b, v103
	v_exp_f32_e32 v0, v0
	v_exp_f32_e32 v102, v102
	v_pk_add_f32 v[104:105], v[104:105], v[136:137]
	v_pk_add_f32 v[100:101], v[100:101], v[132:133]
	v_add_f32_e32 v98, 1.0, v98
	v_add_f32_e32 v111, 1.0, v111
	v_add_f32_e32 v112, 1.0, v112
	v_mul_f32_e32 v103, 0xbfb8aa3b, v104
	v_mul_f32_e32 v104, 0xbfb8aa3b, v105
	v_rcp_f32_e32 v105, v98
	v_add_f32_e32 v98, 1.0, v99
	v_mul_f32_e32 v99, 0xbfb8aa3b, v100
	v_rcp_f32_e32 v111, v111
	v_rcp_f32_e32 v112, v112
	v_exp_f32_e32 v99, v99
	v_mul_f32_e32 v100, 0xbfb8aa3b, v101
	v_add_f32_e32 v0, 1.0, v0
	v_add_f32_e32 v102, 1.0, v102
	v_exp_f32_e32 v100, v100
	v_rcp_f32_e32 v0, v0
	v_rcp_f32_e32 v102, v102
	v_pk_add_f32 v[90:91], v[90:91], v[130:131]
	v_add_co_u32_e32 v110, vcc, s8, v138
	v_mul_f32_e32 v90, 0xbfb8aa3b, v90
	v_cvt_pk_bf16_f32 v107, v111, v112
	v_cvt_pk_bf16_f32 v108, v113, v109
	v_cvt_pk_bf16_f32 v109, v114, v115
	v_addc_co_u32_e32 v111, vcc, 0, v139, vcc
	v_rcp_f32_e32 v101, v98
	v_add_f32_e32 v98, 1.0, v99
	v_exp_f32_e32 v90, v90
	v_mul_f32_e32 v91, 0xbfb8aa3b, v91
	global_store_dwordx4 v[110:111], v[106:109], off
	v_exp_f32_e32 v103, v103
	v_exp_f32_e32 v104, v104
	v_rcp_f32_e32 v106, v98
	v_add_f32_e32 v98, 1.0, v100
	v_pk_add_f32 v[94:95], v[94:95], v[134:135]
	v_exp_f32_e32 v91, v91
	v_rcp_f32_e32 v107, v98
	v_cvt_pk_bf16_f32 v98, v0, v102
	v_mul_f32_e32 v0, 0xbfb8aa3b, v94
	v_mul_f32_e32 v94, 0xbfb8aa3b, v95
	v_exp_f32_e32 v0, v0
	v_exp_f32_e32 v94, v94
	v_pk_add_f32 v[96:97], v[96:97], v[136:137]
	v_pk_add_f32 v[92:93], v[92:93], v[132:133]
	v_add_f32_e32 v90, 1.0, v90
	v_add_f32_e32 v103, 1.0, v103
	v_add_f32_e32 v104, 1.0, v104
	v_mul_f32_e32 v95, 0xbfb8aa3b, v96
	v_mul_f32_e32 v96, 0xbfb8aa3b, v97
	v_rcp_f32_e32 v97, v90
	v_add_f32_e32 v90, 1.0, v91
	v_mul_f32_e32 v91, 0xbfb8aa3b, v92
	v_rcp_f32_e32 v103, v103
	v_rcp_f32_e32 v104, v104
	v_exp_f32_e32 v91, v91
	v_mul_f32_e32 v92, 0xbfb8aa3b, v93
	v_add_f32_e32 v0, 1.0, v0
	v_add_f32_e32 v94, 1.0, v94
	v_exp_f32_e32 v92, v92
	s_movk_i32 s8, 0x6000
	v_rcp_f32_e32 v0, v0
	v_rcp_f32_e32 v94, v94
	v_pk_add_f32 v[82:83], v[82:83], v[130:131]
	v_add_co_u32_e32 v102, vcc, s8, v138
	v_mul_f32_e32 v82, 0xbfb8aa3b, v82
	v_cvt_pk_bf16_f32 v99, v103, v104
	v_cvt_pk_bf16_f32 v100, v105, v101
	v_cvt_pk_bf16_f32 v101, v106, v107
	v_addc_co_u32_e32 v103, vcc, 0, v139, vcc
	v_rcp_f32_e32 v93, v90
	v_add_f32_e32 v90, 1.0, v91
	v_exp_f32_e32 v82, v82
	v_mul_f32_e32 v83, 0xbfb8aa3b, v83
	global_store_dwordx4 v[102:103], v[98:101], off
	v_exp_f32_e32 v95, v95
	v_exp_f32_e32 v96, v96
	v_rcp_f32_e32 v98, v90
	v_add_f32_e32 v90, 1.0, v92
	v_pk_add_f32 v[86:87], v[86:87], v[134:135]
	v_exp_f32_e32 v83, v83
	v_rcp_f32_e32 v99, v90
	v_cvt_pk_bf16_f32 v90, v0, v94
	v_mul_f32_e32 v0, 0xbfb8aa3b, v86
	v_mul_f32_e32 v86, 0xbfb8aa3b, v87
	v_exp_f32_e32 v0, v0
	v_exp_f32_e32 v86, v86
	v_pk_add_f32 v[88:89], v[88:89], v[136:137]
	v_pk_add_f32 v[84:85], v[84:85], v[132:133]
	v_add_f32_e32 v82, 1.0, v82
	v_add_f32_e32 v95, 1.0, v95
	v_add_f32_e32 v96, 1.0, v96
	v_mul_f32_e32 v87, 0xbfb8aa3b, v88
	v_mul_f32_e32 v88, 0xbfb8aa3b, v89
	v_rcp_f32_e32 v89, v82
	v_add_f32_e32 v82, 1.0, v83
	v_mul_f32_e32 v83, 0xbfb8aa3b, v84
	v_rcp_f32_e32 v95, v95
	v_rcp_f32_e32 v96, v96
	v_exp_f32_e32 v83, v83
	v_mul_f32_e32 v84, 0xbfb8aa3b, v85
	v_add_f32_e32 v0, 1.0, v0
	v_add_f32_e32 v86, 1.0, v86
	v_exp_f32_e32 v84, v84
	v_rcp_f32_e32 v0, v0
	v_rcp_f32_e32 v86, v86
	v_pk_add_f32 v[74:75], v[74:75], v[130:131]
	v_add_co_u32_e32 v94, vcc, s16, v138
	v_mul_f32_e32 v74, 0xbfb8aa3b, v74
	v_cvt_pk_bf16_f32 v91, v95, v96
	v_cvt_pk_bf16_f32 v92, v97, v93
	v_cvt_pk_bf16_f32 v93, v98, v99
	v_addc_co_u32_e32 v95, vcc, 0, v139, vcc
	v_rcp_f32_e32 v85, v82
	v_add_f32_e32 v82, 1.0, v83
	v_exp_f32_e32 v74, v74
	v_mul_f32_e32 v75, 0xbfb8aa3b, v75
	global_store_dwordx4 v[94:95], v[90:93], off
	v_exp_f32_e32 v87, v87
	v_exp_f32_e32 v88, v88
	v_rcp_f32_e32 v90, v82
	v_add_f32_e32 v82, 1.0, v84
	v_pk_add_f32 v[78:79], v[78:79], v[134:135]
	v_exp_f32_e32 v75, v75
	v_rcp_f32_e32 v91, v82
	v_cvt_pk_bf16_f32 v82, v0, v86
	v_mul_f32_e32 v0, 0xbfb8aa3b, v78
	v_mul_f32_e32 v78, 0xbfb8aa3b, v79
	v_exp_f32_e32 v0, v0
	v_exp_f32_e32 v78, v78
	v_pk_add_f32 v[80:81], v[80:81], v[136:137]
	v_pk_add_f32 v[76:77], v[76:77], v[132:133]
	v_add_f32_e32 v74, 1.0, v74
	v_add_f32_e32 v87, 1.0, v87
	v_add_f32_e32 v88, 1.0, v88
	v_mul_f32_e32 v79, 0xbfb8aa3b, v80
	v_mul_f32_e32 v80, 0xbfb8aa3b, v81
	v_rcp_f32_e32 v81, v74
	v_add_f32_e32 v74, 1.0, v75
	v_mul_f32_e32 v75, 0xbfb8aa3b, v76
	v_pk_add_f32 v[66:67], v[66:67], v[130:131]
	v_rcp_f32_e32 v87, v87
	v_rcp_f32_e32 v88, v88
	v_exp_f32_e32 v75, v75
	v_mul_f32_e32 v76, 0xbfb8aa3b, v77
	v_mul_f32_e32 v66, 0xbfb8aa3b, v66
	v_add_f32_e32 v0, 1.0, v0
	v_add_f32_e32 v78, 1.0, v78
	v_exp_f32_e32 v76, v76
	v_exp_f32_e32 v66, v66
	v_mul_f32_e32 v67, 0xbfb8aa3b, v67
	s_mov_b32 s8, 0x12000
	v_rcp_f32_e32 v0, v0
	v_exp_f32_e32 v79, v79
	v_exp_f32_e32 v80, v80
	v_rcp_f32_e32 v78, v78
	v_exp_f32_e32 v67, v67
	v_add_co_u32_e32 v86, vcc, s8, v138
	v_cvt_pk_bf16_f32 v83, v87, v88
	v_cvt_pk_bf16_f32 v84, v89, v85
	v_cvt_pk_bf16_f32 v85, v90, v91
	v_addc_co_u32_e32 v87, vcc, 0, v139, vcc
	v_rcp_f32_e32 v77, v74
	v_add_f32_e32 v74, 1.0, v75
	global_store_dwordx4 v[86:87], v[82:85], off
	v_pk_add_f32 v[72:73], v[72:73], v[136:137]
	v_pk_add_f32 v[70:71], v[70:71], v[134:135]
	v_rcp_f32_e32 v82, v74
	v_add_f32_e32 v74, 1.0, v76
	v_pk_add_f32 v[68:69], v[68:69], v[132:133]
	v_add_f32_e32 v66, 1.0, v66
	v_add_f32_e32 v79, 1.0, v79
	v_add_f32_e32 v80, 1.0, v80
	v_rcp_f32_e32 v83, v74
	v_cvt_pk_bf16_f32 v74, v0, v78
	v_mul_f32_e32 v0, 0xbfb8aa3b, v70
	v_mul_f32_e32 v70, 0xbfb8aa3b, v71
	v_mul_f32_e32 v71, 0xbfb8aa3b, v72
	v_mul_f32_e32 v72, 0xbfb8aa3b, v73
	v_rcp_f32_e32 v73, v66
	v_add_f32_e32 v66, 1.0, v67
	v_mul_f32_e32 v67, 0xbfb8aa3b, v68
	v_rcp_f32_e32 v79, v79
	v_rcp_f32_e32 v80, v80
	v_exp_f32_e32 v0, v0
	v_exp_f32_e32 v70, v70
	v_exp_f32_e32 v67, v67
	v_mul_f32_e32 v68, 0xbfb8aa3b, v69
	v_exp_f32_e32 v71, v71
	v_exp_f32_e32 v72, v72
	v_exp_f32_e32 v68, v68
	s_mov_b32 s8, 0x14000
	v_add_co_u32_e32 v78, vcc, s8, v138
	v_cvt_pk_bf16_f32 v75, v79, v80
	v_cvt_pk_bf16_f32 v76, v81, v77
	v_cvt_pk_bf16_f32 v77, v82, v83
	v_addc_co_u32_e32 v79, vcc, 0, v139, vcc
	v_add_f32_e32 v0, 1.0, v0
	v_add_f32_e32 v70, 1.0, v70
	v_rcp_f32_e32 v69, v66
	v_add_f32_e32 v66, 1.0, v67
	global_store_dwordx4 v[78:79], v[74:77], off
	v_rcp_f32_e32 v0, v0
	v_rcp_f32_e32 v70, v70
	v_add_f32_e32 v71, 1.0, v71
	v_add_f32_e32 v72, 1.0, v72
	v_rcp_f32_e32 v74, v66
	v_add_f32_e32 v66, 1.0, v68
	v_rcp_f32_e32 v71, v71
	v_rcp_f32_e32 v72, v72
	v_rcp_f32_e32 v75, v66
	s_mov_b32 s8, 0x16000
	v_cvt_pk_bf16_f32 v66, v0, v70
	v_add_co_u32_e32 v70, vcc, s8, v138
	v_cvt_pk_bf16_f32 v67, v71, v72
	v_cvt_pk_bf16_f32 v68, v73, v69
	v_cvt_pk_bf16_f32 v69, v74, v75
	v_addc_co_u32_e32 v71, vcc, 0, v139, vcc
	global_store_dwordx4 v[70:71], v[66:69], off
	s_mov_b32 s8, 0x8000
	s_nop 1
	v_mov_b32_e32 v70, v150
	v_mov_b32_e32 v71, v151
	v_mov_b32_e32 v72, v152
	v_mov_b32_e32 v73, v153
	v_mov_b32_e32 v66, v154
	v_mov_b32_e32 v67, v155
	v_mov_b32_e32 v68, v156
	v_mov_b32_e32 v69, v157
	v_pk_add_f32 v[62:63], v[62:63], v[70:71]
	v_pk_add_f32 v[58:59], v[58:59], v[66:67]
	v_mul_f32_e32 v0, 0xbfb8aa3b, v62
	v_mul_f32_e32 v58, 0xbfb8aa3b, v58
	v_exp_f32_e32 v58, v58
	v_mul_f32_e32 v59, 0xbfb8aa3b, v59
	v_exp_f32_e32 v59, v59
	v_mul_f32_e32 v62, 0xbfb8aa3b, v63
	v_exp_f32_e32 v0, v0
	v_exp_f32_e32 v62, v62
	v_pk_add_f32 v[64:65], v[64:65], v[72:73]
	v_pk_add_f32 v[60:61], v[60:61], v[68:69]
	v_add_f32_e32 v58, 1.0, v58
	v_mul_f32_e32 v63, 0xbfb8aa3b, v64
	v_mul_f32_e32 v64, 0xbfb8aa3b, v65
	v_rcp_f32_e32 v65, v58
	v_add_f32_e32 v58, 1.0, v59
	v_mul_f32_e32 v59, 0xbfb8aa3b, v60
	v_exp_f32_e32 v59, v59
	v_mul_f32_e32 v60, 0xbfb8aa3b, v61
	v_add_f32_e32 v0, 1.0, v0
	v_add_f32_e32 v62, 1.0, v62
	v_exp_f32_e32 v60, v60
	v_rcp_f32_e32 v0, v0
	v_rcp_f32_e32 v62, v62
	v_pk_add_f32 v[50:51], v[50:51], v[66:67]
	v_rcp_f32_e32 v61, v58
	v_mul_f32_e32 v50, 0xbfb8aa3b, v50
	v_add_f32_e32 v58, 1.0, v59
	v_exp_f32_e32 v50, v50
	v_mul_f32_e32 v51, 0xbfb8aa3b, v51
	v_exp_f32_e32 v63, v63
	v_exp_f32_e32 v64, v64
	v_rcp_f32_e32 v74, v58
	v_add_f32_e32 v58, 1.0, v60
	v_pk_add_f32 v[54:55], v[54:55], v[70:71]
	v_exp_f32_e32 v51, v51
	v_rcp_f32_e32 v75, v58
	v_cvt_pk_bf16_f32 v58, v0, v62
	v_mul_f32_e32 v0, 0xbfb8aa3b, v54
	v_mul_f32_e32 v54, 0xbfb8aa3b, v55
	v_exp_f32_e32 v0, v0
	v_exp_f32_e32 v54, v54
	v_pk_add_f32 v[56:57], v[56:57], v[72:73]
	v_pk_add_f32 v[52:53], v[52:53], v[68:69]
	v_add_f32_e32 v50, 1.0, v50
	v_add_f32_e32 v63, 1.0, v63
	v_add_f32_e32 v64, 1.0, v64
	v_mul_f32_e32 v55, 0xbfb8aa3b, v56
	v_mul_f32_e32 v56, 0xbfb8aa3b, v57
	v_rcp_f32_e32 v57, v50
	v_add_f32_e32 v50, 1.0, v51
	v_mul_f32_e32 v51, 0xbfb8aa3b, v52
	v_rcp_f32_e32 v63, v63
	v_rcp_f32_e32 v64, v64
	v_exp_f32_e32 v51, v51
	v_mul_f32_e32 v52, 0xbfb8aa3b, v53
	v_add_f32_e32 v0, 1.0, v0
	v_add_f32_e32 v54, 1.0, v54
	v_exp_f32_e32 v52, v52
	v_rcp_f32_e32 v0, v0
	v_rcp_f32_e32 v54, v54
	v_pk_add_f32 v[42:43], v[42:43], v[66:67]
	v_add_co_u32_e32 v62, vcc, s8, v138
	v_mul_f32_e32 v42, 0xbfb8aa3b, v42
	v_cvt_pk_bf16_f32 v59, v63, v64
	v_cvt_pk_bf16_f32 v60, v65, v61
	v_cvt_pk_bf16_f32 v61, v74, v75
	v_addc_co_u32_e32 v63, vcc, 0, v139, vcc
	v_rcp_f32_e32 v53, v50
	v_add_f32_e32 v50, 1.0, v51
	v_exp_f32_e32 v42, v42
	v_mul_f32_e32 v43, 0xbfb8aa3b, v43
	global_store_dwordx4 v[62:63], v[58:61], off
	v_exp_f32_e32 v55, v55
	v_exp_f32_e32 v56, v56
	v_rcp_f32_e32 v58, v50
	v_add_f32_e32 v50, 1.0, v52
	v_pk_add_f32 v[46:47], v[46:47], v[70:71]
	v_exp_f32_e32 v43, v43
	v_rcp_f32_e32 v59, v50
	v_cvt_pk_bf16_f32 v50, v0, v54
	v_mul_f32_e32 v0, 0xbfb8aa3b, v46
	v_mul_f32_e32 v46, 0xbfb8aa3b, v47
	v_exp_f32_e32 v0, v0
	v_exp_f32_e32 v46, v46
	v_pk_add_f32 v[48:49], v[48:49], v[72:73]
	v_pk_add_f32 v[44:45], v[44:45], v[68:69]
	v_add_f32_e32 v42, 1.0, v42
	v_add_f32_e32 v55, 1.0, v55
	v_add_f32_e32 v56, 1.0, v56
	v_mul_f32_e32 v47, 0xbfb8aa3b, v48
	v_mul_f32_e32 v48, 0xbfb8aa3b, v49
	v_rcp_f32_e32 v49, v42
	v_add_f32_e32 v42, 1.0, v43
	v_mul_f32_e32 v43, 0xbfb8aa3b, v44
	v_rcp_f32_e32 v55, v55
	v_rcp_f32_e32 v56, v56
	v_exp_f32_e32 v43, v43
	v_mul_f32_e32 v44, 0xbfb8aa3b, v45
	v_add_f32_e32 v0, 1.0, v0
	v_add_f32_e32 v46, 1.0, v46
	v_exp_f32_e32 v44, v44
	s_mov_b32 s8, 0xa000
	v_rcp_f32_e32 v0, v0
	v_rcp_f32_e32 v46, v46
	v_pk_add_f32 v[34:35], v[34:35], v[66:67]
	v_add_co_u32_e32 v54, vcc, s8, v138
	v_mul_f32_e32 v34, 0xbfb8aa3b, v34
	v_cvt_pk_bf16_f32 v51, v55, v56
	v_cvt_pk_bf16_f32 v52, v57, v53
	v_cvt_pk_bf16_f32 v53, v58, v59
	v_addc_co_u32_e32 v55, vcc, 0, v139, vcc
	v_rcp_f32_e32 v45, v42
	v_add_f32_e32 v42, 1.0, v43
	v_exp_f32_e32 v34, v34
	v_mul_f32_e32 v35, 0xbfb8aa3b, v35
	global_store_dwordx4 v[54:55], v[50:53], off
	v_exp_f32_e32 v47, v47
	v_exp_f32_e32 v48, v48
	v_rcp_f32_e32 v50, v42
	v_add_f32_e32 v42, 1.0, v44
	v_pk_add_f32 v[38:39], v[38:39], v[70:71]
	v_exp_f32_e32 v35, v35
	v_rcp_f32_e32 v51, v42
	v_cvt_pk_bf16_f32 v42, v0, v46
	v_mul_f32_e32 v0, 0xbfb8aa3b, v38
	v_mul_f32_e32 v38, 0xbfb8aa3b, v39
	v_exp_f32_e32 v0, v0
	v_exp_f32_e32 v38, v38
	v_pk_add_f32 v[40:41], v[40:41], v[72:73]
	v_pk_add_f32 v[36:37], v[36:37], v[68:69]
	v_add_f32_e32 v34, 1.0, v34
	v_add_f32_e32 v47, 1.0, v47
	v_add_f32_e32 v48, 1.0, v48
	v_mul_f32_e32 v39, 0xbfb8aa3b, v40
	v_mul_f32_e32 v40, 0xbfb8aa3b, v41
	v_rcp_f32_e32 v41, v34
	v_add_f32_e32 v34, 1.0, v35
	v_mul_f32_e32 v35, 0xbfb8aa3b, v36
	v_rcp_f32_e32 v47, v47
	v_rcp_f32_e32 v48, v48
	v_exp_f32_e32 v35, v35
	v_mul_f32_e32 v36, 0xbfb8aa3b, v37
	v_add_f32_e32 v0, 1.0, v0
	v_add_f32_e32 v38, 1.0, v38
	v_exp_f32_e32 v36, v36
	s_mov_b32 s8, 0xc000
	v_rcp_f32_e32 v0, v0
	v_rcp_f32_e32 v38, v38
	v_pk_add_f32 v[26:27], v[26:27], v[66:67]
	v_add_co_u32_e32 v46, vcc, s8, v138
	v_mul_f32_e32 v26, 0xbfb8aa3b, v26
	v_cvt_pk_bf16_f32 v43, v47, v48
	v_cvt_pk_bf16_f32 v44, v49, v45
	v_cvt_pk_bf16_f32 v45, v50, v51
	v_addc_co_u32_e32 v47, vcc, 0, v139, vcc
	v_rcp_f32_e32 v37, v34
	v_add_f32_e32 v34, 1.0, v35
	v_exp_f32_e32 v26, v26
	v_mul_f32_e32 v27, 0xbfb8aa3b, v27
	global_store_dwordx4 v[46:47], v[42:45], off
	v_exp_f32_e32 v39, v39
	v_exp_f32_e32 v40, v40
	v_rcp_f32_e32 v42, v34
	v_add_f32_e32 v34, 1.0, v36
	v_pk_add_f32 v[30:31], v[30:31], v[70:71]
	v_exp_f32_e32 v27, v27
	v_rcp_f32_e32 v43, v34
	v_cvt_pk_bf16_f32 v34, v0, v38
	v_mul_f32_e32 v0, 0xbfb8aa3b, v30
	v_mul_f32_e32 v30, 0xbfb8aa3b, v31
	v_exp_f32_e32 v0, v0
	v_exp_f32_e32 v30, v30
	v_pk_add_f32 v[32:33], v[32:33], v[72:73]
	v_pk_add_f32 v[28:29], v[28:29], v[68:69]
	v_add_f32_e32 v26, 1.0, v26
	v_add_f32_e32 v39, 1.0, v39
	v_add_f32_e32 v40, 1.0, v40
	v_mul_f32_e32 v31, 0xbfb8aa3b, v32
	v_mul_f32_e32 v32, 0xbfb8aa3b, v33
	v_rcp_f32_e32 v33, v26
	v_add_f32_e32 v26, 1.0, v27
	v_mul_f32_e32 v27, 0xbfb8aa3b, v28
	v_rcp_f32_e32 v39, v39
	v_rcp_f32_e32 v40, v40
	v_exp_f32_e32 v27, v27
	v_mul_f32_e32 v28, 0xbfb8aa3b, v29
	v_add_f32_e32 v0, 1.0, v0
	v_add_f32_e32 v30, 1.0, v30
	v_exp_f32_e32 v28, v28
	s_mov_b32 s8, 0xe000
	v_rcp_f32_e32 v0, v0
	v_rcp_f32_e32 v30, v30
	v_pk_add_f32 v[18:19], v[18:19], v[66:67]
	v_add_co_u32_e32 v38, vcc, s8, v138
	v_mul_f32_e32 v18, 0xbfb8aa3b, v18
	v_cvt_pk_bf16_f32 v35, v39, v40
	v_cvt_pk_bf16_f32 v36, v41, v37
	v_cvt_pk_bf16_f32 v37, v42, v43
	v_addc_co_u32_e32 v39, vcc, 0, v139, vcc
	v_rcp_f32_e32 v29, v26
	v_add_f32_e32 v26, 1.0, v27
	v_exp_f32_e32 v18, v18
	v_mul_f32_e32 v19, 0xbfb8aa3b, v19
	global_store_dwordx4 v[38:39], v[34:37], off
	v_exp_f32_e32 v31, v31
	v_exp_f32_e32 v32, v32
	v_rcp_f32_e32 v34, v26
	v_add_f32_e32 v26, 1.0, v28
	v_pk_add_f32 v[22:23], v[22:23], v[70:71]
	v_exp_f32_e32 v19, v19
	v_rcp_f32_e32 v35, v26
	v_cvt_pk_bf16_f32 v26, v0, v30
	v_mul_f32_e32 v0, 0xbfb8aa3b, v22
	v_mul_f32_e32 v22, 0xbfb8aa3b, v23
	v_exp_f32_e32 v0, v0
	v_exp_f32_e32 v22, v22
	v_pk_add_f32 v[24:25], v[24:25], v[72:73]
	v_pk_add_f32 v[20:21], v[20:21], v[68:69]
	v_add_f32_e32 v18, 1.0, v18
	v_add_f32_e32 v31, 1.0, v31
	v_add_f32_e32 v32, 1.0, v32
	v_mul_f32_e32 v23, 0xbfb8aa3b, v24
	v_mul_f32_e32 v24, 0xbfb8aa3b, v25
	v_rcp_f32_e32 v25, v18
	v_add_f32_e32 v18, 1.0, v19
	v_mul_f32_e32 v19, 0xbfb8aa3b, v20
	v_rcp_f32_e32 v31, v31
	v_rcp_f32_e32 v32, v32
	v_exp_f32_e32 v19, v19
	v_mul_f32_e32 v20, 0xbfb8aa3b, v21
	v_add_f32_e32 v0, 1.0, v0
	v_add_f32_e32 v22, 1.0, v22
	v_exp_f32_e32 v20, v20
	s_mov_b32 s8, 0x18000
	v_rcp_f32_e32 v0, v0
	v_rcp_f32_e32 v22, v22
	v_pk_add_f32 v[10:11], v[10:11], v[66:67]
	v_add_co_u32_e32 v30, vcc, s8, v138
	v_mul_f32_e32 v10, 0xbfb8aa3b, v10
	v_cvt_pk_bf16_f32 v27, v31, v32
	v_cvt_pk_bf16_f32 v28, v33, v29
	v_cvt_pk_bf16_f32 v29, v34, v35
	v_addc_co_u32_e32 v31, vcc, 0, v139, vcc
	v_rcp_f32_e32 v21, v18
	v_add_f32_e32 v18, 1.0, v19
	v_exp_f32_e32 v10, v10
	v_mul_f32_e32 v11, 0xbfb8aa3b, v11
	global_store_dwordx4 v[30:31], v[26:29], off
	v_exp_f32_e32 v23, v23
	v_exp_f32_e32 v24, v24
	v_rcp_f32_e32 v26, v18
	v_add_f32_e32 v18, 1.0, v20
	v_pk_add_f32 v[14:15], v[14:15], v[70:71]
	v_exp_f32_e32 v11, v11
	v_rcp_f32_e32 v27, v18
	v_cvt_pk_bf16_f32 v18, v0, v22
	v_mul_f32_e32 v0, 0xbfb8aa3b, v14
	v_mul_f32_e32 v14, 0xbfb8aa3b, v15
	v_exp_f32_e32 v0, v0
	v_exp_f32_e32 v14, v14
	v_pk_add_f32 v[16:17], v[16:17], v[72:73]
	v_pk_add_f32 v[12:13], v[12:13], v[68:69]
	v_add_f32_e32 v10, 1.0, v10
	v_add_f32_e32 v23, 1.0, v23
	v_add_f32_e32 v24, 1.0, v24
	v_mul_f32_e32 v15, 0xbfb8aa3b, v16
	v_mul_f32_e32 v16, 0xbfb8aa3b, v17
	v_rcp_f32_e32 v17, v10
	v_add_f32_e32 v10, 1.0, v11
	v_mul_f32_e32 v11, 0xbfb8aa3b, v12
	v_pk_add_f32 v[2:3], v[2:3], v[66:67]
	v_rcp_f32_e32 v23, v23
	v_rcp_f32_e32 v24, v24
	v_exp_f32_e32 v11, v11
	v_mul_f32_e32 v12, 0xbfb8aa3b, v13
	v_mul_f32_e32 v2, 0xbfb8aa3b, v2
	v_add_f32_e32 v0, 1.0, v0
	v_add_f32_e32 v14, 1.0, v14
	v_exp_f32_e32 v12, v12
	v_exp_f32_e32 v2, v2
	v_mul_f32_e32 v3, 0xbfb8aa3b, v3
	s_mov_b32 s8, 0x1a000
	v_rcp_f32_e32 v0, v0
	v_exp_f32_e32 v15, v15
	v_exp_f32_e32 v16, v16
	v_rcp_f32_e32 v14, v14
	v_exp_f32_e32 v3, v3
	v_add_co_u32_e32 v22, vcc, s8, v138
	v_cvt_pk_bf16_f32 v19, v23, v24
	v_cvt_pk_bf16_f32 v20, v25, v21
	v_cvt_pk_bf16_f32 v21, v26, v27
	v_addc_co_u32_e32 v23, vcc, 0, v139, vcc
	v_rcp_f32_e32 v13, v10
	v_add_f32_e32 v10, 1.0, v11
	global_store_dwordx4 v[22:23], v[18:21], off
	v_pk_add_f32 v[8:9], v[8:9], v[72:73]
	v_pk_add_f32 v[6:7], v[6:7], v[70:71]
	v_rcp_f32_e32 v18, v10
	v_add_f32_e32 v10, 1.0, v12
	v_pk_add_f32 v[4:5], v[4:5], v[68:69]
	v_add_f32_e32 v2, 1.0, v2
	v_add_f32_e32 v15, 1.0, v15
	v_add_f32_e32 v16, 1.0, v16
	v_rcp_f32_e32 v19, v10
	v_cvt_pk_bf16_f32 v10, v0, v14
	v_mul_f32_e32 v0, 0xbfb8aa3b, v6
	v_mul_f32_e32 v6, 0xbfb8aa3b, v7
	v_mul_f32_e32 v7, 0xbfb8aa3b, v8
	v_mul_f32_e32 v8, 0xbfb8aa3b, v9
	v_rcp_f32_e32 v9, v2
	v_add_f32_e32 v2, 1.0, v3
	v_mul_f32_e32 v3, 0xbfb8aa3b, v4
	v_rcp_f32_e32 v15, v15
	v_rcp_f32_e32 v16, v16
	v_exp_f32_e32 v0, v0
	v_exp_f32_e32 v6, v6
	v_exp_f32_e32 v3, v3
	v_mul_f32_e32 v4, 0xbfb8aa3b, v5
	v_exp_f32_e32 v7, v7
	v_exp_f32_e32 v8, v8
	v_exp_f32_e32 v4, v4
	s_mov_b32 s8, 0x1c000
	v_add_co_u32_e32 v14, vcc, s8, v138
	v_cvt_pk_bf16_f32 v11, v15, v16
	v_cvt_pk_bf16_f32 v12, v17, v13
	v_cvt_pk_bf16_f32 v13, v18, v19
	v_addc_co_u32_e32 v15, vcc, 0, v139, vcc
	v_add_f32_e32 v0, 1.0, v0
	v_add_f32_e32 v6, 1.0, v6
	v_rcp_f32_e32 v5, v2
	v_add_f32_e32 v2, 1.0, v3
	global_store_dwordx4 v[14:15], v[10:13], off
	v_rcp_f32_e32 v0, v0
	v_rcp_f32_e32 v6, v6
	v_add_f32_e32 v7, 1.0, v7
	v_add_f32_e32 v8, 1.0, v8
	v_rcp_f32_e32 v10, v2
	v_add_f32_e32 v2, 1.0, v4
	v_rcp_f32_e32 v7, v7
	v_rcp_f32_e32 v8, v8
	v_rcp_f32_e32 v11, v2
	v_cvt_pk_bf16_f32 v2, v0, v6
	v_add_co_u32_e32 v6, vcc, 0x1e000, v138
	v_cvt_pk_bf16_f32 v3, v7, v8
	v_cvt_pk_bf16_f32 v4, v9, v5
	v_cvt_pk_bf16_f32 v5, v10, v11
	v_addc_co_u32_e32 v7, vcc, 0, v139, vcc
	global_store_dwordx4 v[6:7], v[2:5], off
	s_branch .LBB0_1140
